# attention steady loop: v18 (G prefetch + packed subtracts) with the first QK MFMA issued right after the first block of subtracts
# speedup vs baseline: 1.0033x; 1.0019x over previous
.LBB0_1341:
	v_sub_f32_e32 v186, v214, v217
	s_waitcnt lgkmcnt(4)
	v_pk_add_f32 v[110:111], v[186:187], v[222:223] op_sel_hi:[0,1] neg_lo:[0,1] neg_hi:[0,1]
	v_pk_add_f32 v[108:109], v[186:187], v[220:221] op_sel_hi:[0,1] neg_lo:[0,1] neg_hi:[0,1]
	v_pk_add_f32 v[106:107], v[186:187], v[198:199] op_sel_hi:[0,1] neg_lo:[0,1] neg_hi:[0,1]
	v_pk_add_f32 v[104:105], v[186:187], v[196:197] op_sel_hi:[0,1] neg_lo:[0,1] neg_hi:[0,1]
	v_pk_add_f32 v[102:103], v[186:187], v[194:195] op_sel_hi:[0,1] neg_lo:[0,1] neg_hi:[0,1]
	v_pk_add_f32 v[100:101], v[186:187], v[192:193] op_sel_hi:[0,1] neg_lo:[0,1] neg_hi:[0,1]
	v_pk_add_f32 v[98:99], v[186:187], v[190:191] op_sel_hi:[0,1] neg_lo:[0,1] neg_hi:[0,1]
	v_pk_add_f32 v[96:97], v[186:187], v[188:189] op_sel_hi:[0,1] neg_lo:[0,1] neg_hi:[0,1]
	v_add_u32_e32 v0, s8, v216
	ds_read_b64_tr_b16 v[4:5], v0 offset:24576
	ds_read_b64_tr_b16 v[6:7], v0 offset:25088
	v_mfma_f32_32x32x16_bf16 v[96:111], v[172:175], v[124:127], v[96:111]
	s_waitcnt lgkmcnt(2)
	v_pk_add_f32 v[94:95], v[186:187], v[238:239] op_sel_hi:[0,1] neg_lo:[0,1] neg_hi:[0,1]
	v_pk_add_f32 v[92:93], v[186:187], v[236:237] op_sel_hi:[0,1] neg_lo:[0,1] neg_hi:[0,1]
	v_pk_add_f32 v[90:91], v[186:187], v[234:235] op_sel_hi:[0,1] neg_lo:[0,1] neg_hi:[0,1]
	v_pk_add_f32 v[88:89], v[186:187], v[232:233] op_sel_hi:[0,1] neg_lo:[0,1] neg_hi:[0,1]
	v_pk_add_f32 v[86:87], v[186:187], v[230:231] op_sel_hi:[0,1] neg_lo:[0,1] neg_hi:[0,1]
	v_pk_add_f32 v[84:85], v[186:187], v[228:229] op_sel_hi:[0,1] neg_lo:[0,1] neg_hi:[0,1]
	v_pk_add_f32 v[82:83], v[186:187], v[226:227] op_sel_hi:[0,1] neg_lo:[0,1] neg_hi:[0,1]
	v_pk_add_f32 v[80:81], v[186:187], v[224:225] op_sel_hi:[0,1] neg_lo:[0,1] neg_hi:[0,1]
	ds_read_b128 v[188:191], v180 offset:256
	ds_read_b128 v[192:195], v180 offset:288
	ds_read_b128 v[196:199], v180 offset:320
	ds_read_b128 v[220:223], v180 offset:352
	ds_read_b128 v[224:227], v180 offset:384
	ds_read_b128 v[228:231], v180 offset:416
	ds_read_b128 v[232:235], v180 offset:448
	ds_read_b128 v[236:239], v180 offset:480
	v_add_f32_e32 v1, v64, v65
	v_add_f32_e32 v1, v66, v1
	v_add_f32_e32 v1, v67, v1
	v_add_f32_e32 v1, v68, v1
	v_add_f32_e32 v1, v69, v1
	v_cvt_pk_bf16_f32 v140, v64, v65
	v_cvt_pk_bf16_f32 v141, v66, v67
	ds_read_b64_tr_b16 v[8:9], v0 offset:28672
	ds_read_b64_tr_b16 v[10:11], v0 offset:29184
	v_mfma_f32_32x32x16_bf16 v[80:95], v[168:171], v[124:127], v[80:95]
	v_add_f32_e32 v1, v70, v1
	v_add_f32_e32 v1, v71, v1
	v_add_f32_e32 v1, v72, v1
	v_add_f32_e32 v1, v73, v1
	v_cvt_pk_bf16_f32 v142, v68, v69
	v_cvt_pk_bf16_f32 v143, v70, v71
	ds_read_b64_tr_b16 v[12:13], v0 offset:25600
	ds_read_b64_tr_b16 v[14:15], v0 offset:26112
	v_mfma_f32_32x32x16_bf16 v[96:111], v[164:167], v[120:123], v[96:111]
	v_add_f32_e32 v1, v74, v1
	v_add_f32_e32 v1, v75, v1
	v_add_f32_e32 v1, v76, v1
	v_add_f32_e32 v1, v77, v1
	v_cvt_pk_bf16_f32 v136, v72, v73
	v_cvt_pk_bf16_f32 v137, v74, v75
	ds_read_b64_tr_b16 v[64:65], v0 offset:29696
	ds_read_b64_tr_b16 v[66:67], v0 offset:30208
	v_mfma_f32_32x32x16_bf16 v[80:95], v[160:163], v[120:123], v[80:95]
	v_add_f32_e32 v1, v78, v1
	v_add_f32_e32 v1, v79, v1
	v_add_f32_e32 v1, v48, v1
	v_add_f32_e32 v1, v49, v1
	v_cvt_pk_bf16_f32 v138, v76, v77
	v_cvt_pk_bf16_f32 v139, v78, v79
	ds_read_b64_tr_b16 v[68:69], v0 offset:26624
	ds_read_b64_tr_b16 v[70:71], v0 offset:27136
	v_mfma_f32_32x32x16_bf16 v[96:111], v[156:159], v[116:119], v[96:111]
	v_add_f32_e32 v1, v50, v1
	v_add_f32_e32 v1, v51, v1
	v_add_f32_e32 v1, v52, v1
	v_add_f32_e32 v1, v53, v1
	v_cvt_pk_bf16_f32 v132, v48, v49
	v_cvt_pk_bf16_f32 v133, v50, v51
	ds_read_b64_tr_b16 v[48:49], v0 offset:30720
	ds_read_b64_tr_b16 v[50:51], v0 offset:31232
	v_mfma_f32_32x32x16_bf16 v[80:95], v[152:155], v[116:119], v[80:95]
	v_add_f32_e32 v1, v54, v1
	v_add_f32_e32 v1, v55, v1
	v_add_f32_e32 v1, v56, v1
	v_add_f32_e32 v1, v57, v1
	v_cvt_pk_bf16_f32 v134, v52, v53
	v_cvt_pk_bf16_f32 v135, v54, v55
	ds_read_b64_tr_b16 v[52:53], v0 offset:27648
	ds_read_b64_tr_b16 v[54:55], v0 offset:28160
	v_mfma_f32_32x32x16_bf16 v[96:111], v[148:151], v[112:115], v[96:111]
	v_add_f32_e32 v1, v58, v1
	v_add_f32_e32 v1, v59, v1
	v_add_f32_e32 v1, v60, v1
	v_add_f32_e32 v1, v61, v1
	v_cvt_pk_bf16_f32 v128, v56, v57
	v_cvt_pk_bf16_f32 v129, v58, v59
	ds_read_b64_tr_b16 v[56:57], v0 offset:31744
	ds_read_b64_tr_b16 v[58:59], v0 offset:32256
	v_mfma_f32_32x32x16_bf16 v[80:95], v[144:147], v[112:115], v[80:95]
	v_add_f32_e32 v0, v62, v1
	v_add_f32_e32 v0, v63, v0
	v_add_f32_e32 v2, 0, v0
	v_cvt_pk_bf16_f32 v130, v60, v61
	v_cvt_pk_bf16_f32 v131, v62, v63
	s_mov_b32 s8, 0xfffe0000
	s_mov_b32 s9, -1
	v_lshl_add_u64 v[0:1], v[178:179], 0, s[8:9]
	s_add_i32 s0, s16, s21
	s_mov_b32 s4, m0
	s_mov_b32 m0, s0
	s_nop 0
	global_load_lds_dwordx4 v[0:1], off
	s_mov_b32 m0, s4
	v_lshl_add_u64 v[0:1], v[176:177], 0, s[8:9]
	s_add_i32 s0, s14, s22
	s_mov_b32 s4, m0
	s_mov_b32 m0, s0
	s_nop 0
	global_load_lds_dwordx4 v[0:1], off
	s_mov_b32 m0, s4
	v_max_f32_e32 v0, v97, v97
	v_max_f32_e32 v1, v96, v96
	v_max_f32_e32 v0, v1, v0
	v_max3_f32 v1, v98, v99, v81
	v_max3_f32 v0, v0, v80, v82
	v_max3_f32 v0, v0, v83, v100
	v_max3_f32 v1, v1, v102, v103
	v_max3_f32 v0, v0, v101, v84
	v_max3_f32 v1, v1, v86, v87
	v_max3_f32 v0, v0, v85, v104
	v_max3_f32 v1, v1, v106, v107
	v_max3_f32 v0, v0, v105, v88
	v_max3_f32 v1, v1, v90, v91
	v_max3_f32 v0, v0, v89, v108
	v_max3_f32 v1, v1, v110, v111
	v_max3_f32 v60, v0, v109, v92
	v_max3_f32 v1, v1, v94, v95
	v_max3_f32 v1, v60, v93, v1
	v_add_f32_e32 v0, v218, v2
	v_mov_b32_e32 v2, v1
	s_nop 1
	v_permlane32_swap_b32_e32 v1, v2
	v_max_f32_e32 v2, v2, v2
	v_max_f32_e32 v1, v1, v1
	v_max_f32_e32 v1, v1, v2
	v_cmp_lt_f32_e32 vcc, s33, v1
	s_cmp_lg_u64 vcc, 0
	s_cselect_b64 s[8:9], -1, 0
	s_cbranch_vccnz .LBB0_1349

.LBB0_1344:
	s_add_i32 s0, s14, 0x2000
	s_cmpk_lg_i32 s14, 0x4000
	s_cselect_b32 s25, s0, 0
	v_sub_f32_e32 v186, v214, v217
	s_waitcnt lgkmcnt(4)
	v_pk_add_f32 v[78:79], v[186:187], v[222:223] op_sel_hi:[0,1] neg_lo:[0,1] neg_hi:[0,1]
	v_pk_add_f32 v[76:77], v[186:187], v[220:221] op_sel_hi:[0,1] neg_lo:[0,1] neg_hi:[0,1]
	v_pk_add_f32 v[74:75], v[186:187], v[198:199] op_sel_hi:[0,1] neg_lo:[0,1] neg_hi:[0,1]
	v_pk_add_f32 v[72:73], v[186:187], v[196:197] op_sel_hi:[0,1] neg_lo:[0,1] neg_hi:[0,1]
	v_pk_add_f32 v[70:71], v[186:187], v[194:195] op_sel_hi:[0,1] neg_lo:[0,1] neg_hi:[0,1]
	v_pk_add_f32 v[68:69], v[186:187], v[192:193] op_sel_hi:[0,1] neg_lo:[0,1] neg_hi:[0,1]
	v_pk_add_f32 v[66:67], v[186:187], v[190:191] op_sel_hi:[0,1] neg_lo:[0,1] neg_hi:[0,1]
	v_pk_add_f32 v[64:65], v[186:187], v[188:189] op_sel_hi:[0,1] neg_lo:[0,1] neg_hi:[0,1]
	v_add_u32_e32 v1, s16, v216
	ds_read_b64_tr_b16 v[152:153], v1 offset:24576
	ds_read_b64_tr_b16 v[154:155], v1 offset:25088
	v_mfma_f32_32x32x16_bf16 v[64:79], v[164:167], v[124:127], v[64:79]
	s_waitcnt lgkmcnt(2)
	v_pk_add_f32 v[62:63], v[186:187], v[238:239] op_sel_hi:[0,1] neg_lo:[0,1] neg_hi:[0,1]
	v_pk_add_f32 v[60:61], v[186:187], v[236:237] op_sel_hi:[0,1] neg_lo:[0,1] neg_hi:[0,1]
	v_pk_add_f32 v[58:59], v[186:187], v[234:235] op_sel_hi:[0,1] neg_lo:[0,1] neg_hi:[0,1]
	v_pk_add_f32 v[56:57], v[186:187], v[232:233] op_sel_hi:[0,1] neg_lo:[0,1] neg_hi:[0,1]
	v_pk_add_f32 v[54:55], v[186:187], v[230:231] op_sel_hi:[0,1] neg_lo:[0,1] neg_hi:[0,1]
	v_pk_add_f32 v[52:53], v[186:187], v[228:229] op_sel_hi:[0,1] neg_lo:[0,1] neg_hi:[0,1]
	v_pk_add_f32 v[50:51], v[186:187], v[226:227] op_sel_hi:[0,1] neg_lo:[0,1] neg_hi:[0,1]
	v_pk_add_f32 v[48:49], v[186:187], v[224:225] op_sel_hi:[0,1] neg_lo:[0,1] neg_hi:[0,1]
	ds_read_b128 v[188:191], v180 offset:512
	ds_read_b128 v[192:195], v180 offset:544
	ds_read_b128 v[196:199], v180 offset:576
	ds_read_b128 v[220:223], v180 offset:608
	ds_read_b128 v[224:227], v180 offset:640
	ds_read_b128 v[228:231], v180 offset:672
	ds_read_b128 v[232:235], v180 offset:704
	ds_read_b128 v[236:239], v180 offset:736
	v_add_f32_e32 v2, v96, v97
	v_add_f32_e32 v2, v98, v2
	v_add_f32_e32 v2, v99, v2
	v_add_f32_e32 v2, v100, v2
	v_add_f32_e32 v2, v101, v2
	v_cvt_pk_bf16_f32 v140, v96, v97
	v_cvt_pk_bf16_f32 v141, v98, v99
	ds_read_b64_tr_b16 v[96:97], v1 offset:28672
	ds_read_b64_tr_b16 v[98:99], v1 offset:29184
	v_mfma_f32_32x32x16_bf16 v[48:63], v[160:163], v[124:127], v[48:63]
	v_add_f32_e32 v2, v102, v2
	v_add_f32_e32 v2, v103, v2
	v_add_f32_e32 v2, v104, v2
	v_add_f32_e32 v2, v105, v2
	v_cvt_pk_bf16_f32 v142, v100, v101
	v_cvt_pk_bf16_f32 v143, v102, v103
	ds_read_b64_tr_b16 v[100:101], v1 offset:25600
	ds_read_b64_tr_b16 v[102:103], v1 offset:26112
	v_mfma_f32_32x32x16_bf16 v[64:79], v[156:159], v[120:123], v[64:79]
	v_add_f32_e32 v2, v106, v2
	v_add_f32_e32 v2, v107, v2
	v_add_f32_e32 v2, v108, v2
	v_add_f32_e32 v2, v109, v2
	v_cvt_pk_bf16_f32 v136, v104, v105
	v_cvt_pk_bf16_f32 v137, v106, v107
	ds_read_b64_tr_b16 v[104:105], v1 offset:29696
	ds_read_b64_tr_b16 v[106:107], v1 offset:30208
	v_mfma_f32_32x32x16_bf16 v[48:63], v[148:151], v[120:123], v[48:63]
	v_add_f32_e32 v2, v110, v2
	v_add_f32_e32 v2, v111, v2
	v_add_f32_e32 v2, v80, v2
	v_add_f32_e32 v2, v81, v2
	v_cvt_pk_bf16_f32 v138, v108, v109
	v_cvt_pk_bf16_f32 v139, v110, v111
	ds_read_b64_tr_b16 v[108:109], v1 offset:26624
	ds_read_b64_tr_b16 v[110:111], v1 offset:27136
	v_mfma_f32_32x32x16_bf16 v[64:79], v[144:147], v[116:119], v[64:79]
	v_add_f32_e32 v2, v82, v2
	v_add_f32_e32 v2, v83, v2
	v_add_f32_e32 v2, v84, v2
	v_add_f32_e32 v2, v85, v2
	v_cvt_pk_bf16_f32 v132, v80, v81
	v_cvt_pk_bf16_f32 v133, v82, v83
	ds_read_b64_tr_b16 v[80:81], v1 offset:30720
	ds_read_b64_tr_b16 v[82:83], v1 offset:31232
	v_mfma_f32_32x32x16_bf16 v[48:63], v[12:15], v[116:119], v[48:63]
	v_add_f32_e32 v2, v86, v2
	v_add_f32_e32 v2, v87, v2
	v_add_f32_e32 v2, v88, v2
	v_add_f32_e32 v2, v89, v2
	v_cvt_pk_bf16_f32 v134, v84, v85
	v_cvt_pk_bf16_f32 v135, v86, v87
	ds_read_b64_tr_b16 v[12:13], v1 offset:27648
	ds_read_b64_tr_b16 v[14:15], v1 offset:28160
	v_mfma_f32_32x32x16_bf16 v[64:79], v[8:11], v[112:115], v[64:79]
	v_add_f32_e32 v2, v90, v2
	v_add_f32_e32 v2, v91, v2
	v_add_f32_e32 v2, v92, v2
	v_add_f32_e32 v2, v93, v2
	v_cvt_pk_bf16_f32 v128, v88, v89
	v_cvt_pk_bf16_f32 v129, v90, v91
	ds_read_b64_tr_b16 v[8:9], v1 offset:31744
	ds_read_b64_tr_b16 v[10:11], v1 offset:32256
	v_mfma_f32_32x32x16_bf16 v[48:63], v[4:7], v[112:115], v[48:63]
	v_add_f32_e32 v1, v94, v2
	v_add_f32_e32 v1, v95, v1
	v_add_f32_e32 v1, 0, v1
	v_cvt_pk_bf16_f32 v130, v92, v93
	v_cvt_pk_bf16_f32 v131, v94, v95
	v_max_f32_e32 v2, v65, v65
	v_max_f32_e32 v4, v64, v64
	v_max_f32_e32 v2, v4, v2
	s_nop 3
	v_max3_f32 v4, v66, v67, v49
	v_max3_f32 v2, v2, v48, v50
	v_max3_f32 v2, v2, v51, v68
	v_max3_f32 v4, v4, v70, v71
	v_max3_f32 v2, v2, v69, v52
	v_max3_f32 v4, v4, v54, v55
	v_max3_f32 v2, v2, v53, v72
	v_max3_f32 v4, v4, v74, v75
	v_max3_f32 v2, v2, v73, v56
	v_max3_f32 v4, v4, v58, v59
	v_max3_f32 v2, v2, v57, v76
	v_max3_f32 v4, v4, v78, v79
	v_max3_f32 v2, v2, v77, v60
	v_max3_f32 v4, v4, v62, v63
	v_add_f32_e32 v218, v0, v1
	v_max3_f32 v0, v2, v61, v4
	v_mov_b32_e32 v1, v0
	s_nop 1
	v_permlane32_swap_b32_e32 v0, v1
	v_max_f32_e32 v1, v1, v1
	v_max_f32_e32 v0, v0, v0
	s_add_i32 s0, s14, s21
	s_mov_b32 s4, m0
	s_mov_b32 m0, s0
	s_nop 0
	global_load_lds_dwordx4 v[178:179], off
	s_mov_b32 m0, s4
	v_max_f32_e32 v0, v0, v1
	s_add_i32 s0, s25, s22
	s_mov_b32 s4, m0
	s_mov_b32 m0, s0
	s_nop 0
	global_load_lds_dwordx4 v[176:177], off
	s_mov_b32 m0, s4
	v_cmp_lt_f32_e32 vcc, s33, v0
	s_cmp_lg_u64 vcc, 0
	s_cselect_b64 s[8:9], -1, 0
	s_cbranch_vccnz .LBB0_1352
